# MoBA: 2-pair barrier ring plus the 4 LDS-DMA pieces issued back to back after the last QK MFMA instead of between QK MFMAs and ds_reads
# speedup vs baseline: 1.0151x; 1.0151x over previous
; #define LAS __attribute__((address_space(3)))
; #define MFMA32(a, b, c) __builtin_amdgcn_mfma_f32_32x32x16_bf16((a), (b), (c), 0, 0, 0)
; #define DMA_PAIR(u_, pb_) do { DMA16(kgu + (size_t)(2 * (u_)) * 4096 + so, (pb_)); DMA16(kgu + (size_t)(2 * (u_) + 1) * 4096 + so, (pb_) + 8192); DMA16(vgu + (size_t)(2 * (u_)) * 4096 + so, 32768 + (pb_)); DMA16(vgu + (size_t)(2 * (u_) + 1) * 4096 + so, 32768 + (pb_) + 8192); } while (0)
; template <int l> __device__ __forceinline__ void layer_body(const Args& args, LAS unsigned char* lds, const XcdBarrier& bar) {
;     ...
;                     for (int u = 0; u <= umax; ++u) {
;                         if (u < umax) DMA_PAIR(u + 1, ((u + 1) & 1) * 16384);
;                         if (2 * u <= j) {
;                             const int ta = 2 * u; const bool hasb = (ta + 1 <= j);
;                             const LAS bf16* kl = (const LAS bf16*)(lds + (u & 1) * 16384) + (hh * 32 + pr) * 8; const LAS bf16* vl = (const LAS bf16*)(lds + 32768 + (u & 1) * 16384) + (hh * 128 + r) * 8;
;                             f32x16 st0, st1;
;                             { bf16x8 kfa[8], kfb[8];
; #pragma unroll
;                               for (int s = 0; s < 8; ++s) { kfa[s] = *(const LAS bf16x8*)(kl + s * 512); kfb[s] = *(const LAS bf16x8*)(kl + 4096 + s * 512); }
; #pragma unroll
;                               for (int i = 0; i < 16; ++i) { st0[i] = 0.f; st1[i] = 0.f; }
; #pragma unroll
;                               for (int s = 0; s < 8; ++s) { st0 = MFMA32(kfa[s], qf[s], st0); st1 = MFMA32(kfb[s], qf[s], st1); } }
.LBB0_1510:
	s_cmp_gt_i32 s63, s61
	s_cbranch_scc1 .Lmoba_skipdma
	s_cmp_ge_i32 s75, s65
	s_cbranch_scc1 .Lmoba_qk_nodma
	s_and_b32 s76, s48, 0x4000
	s_and_b32 s50, s48, 0x8000
	s_lshl_b32 s50, s50, 1
	s_or_b32 s76, s76, s50
	v_add_u32_e32 v1, s76, v145
	ds_read_b128 v[218:221], v1
	ds_read_b128 v[222:225], v1 offset:8192
	ds_read_b128 v[226:229], v1 offset:1024
	ds_read_b128 v[230:233], v1 offset:9216
	ds_read_b128 v[234:237], v1 offset:2048
	ds_read_b128 v[238:241], v1 offset:10240
	ds_read_b128 v[242:245], v1 offset:3072
	ds_read_b128 v[246:249], v1 offset:11264
	s_lshr_b32 s77, s75, 2
	v_add_u32_e32 v202, s76, v179
	s_and_b32 s10, s48, 0x4000
	s_xor_b32 s50, s48, 0x8000
	s_and_b32 s50, s50, 0x8000
	s_lshl_b32 s50, s50, 1
	s_or_b32 s10, s10, s50
	s_add_i32 s10, s33, s10
	s_add_u32 s100, s48, 0x4000
	s_addc_u32 s101, s49, 0
	v_lshl_add_u64 v[2:3], v[156:157], 0, s[100:101]
	v_lshl_add_u64 v[4:5], v[2:3], 0, s[36:37]
	v_lshl_add_u64 v[6:7], v[2:3], 0, s[38:39]
	v_lshl_add_u64 v[8:9], v[2:3], 0, s[42:43]
	v_lshl_add_u64 v[10:11], v[2:3], 0, s[44:45]
	s_waitcnt lgkmcnt(7)
	v_mfma_f32_32x32x16_bf16 v[80:95], v[218:221], v[112:115], 0
	ds_read_b128 v[218:221], v1 offset:4096
	s_waitcnt lgkmcnt(7)
	v_mfma_f32_32x32x16_bf16 v[96:111], v[222:225], v[112:115], 0
	ds_read_b128 v[222:225], v1 offset:12288
	s_waitcnt lgkmcnt(7)
	v_mfma_f32_32x32x16_bf16 v[80:95], v[226:229], v[116:119], v[80:95]
	ds_read_b128 v[226:229], v1 offset:5120
	s_waitcnt lgkmcnt(7)
	v_mfma_f32_32x32x16_bf16 v[96:111], v[230:233], v[116:119], v[96:111]
	ds_read_b128 v[230:233], v1 offset:13312
	s_waitcnt lgkmcnt(7)
	v_mfma_f32_32x32x16_bf16 v[80:95], v[234:237], v[120:123], v[80:95]
	ds_read_b128 v[234:237], v1 offset:6144
	s_waitcnt lgkmcnt(7)
	v_mfma_f32_32x32x16_bf16 v[96:111], v[238:241], v[120:123], v[96:111]
	ds_read_b128 v[238:241], v1 offset:14336
	s_waitcnt lgkmcnt(7)
	v_mfma_f32_32x32x16_bf16 v[80:95], v[242:245], v[124:127], v[80:95]
	ds_read_b128 v[242:245], v1 offset:7168
	s_waitcnt lgkmcnt(7)
	v_mfma_f32_32x32x16_bf16 v[96:111], v[246:249], v[124:127], v[96:111]
	ds_read_b128 v[246:249], v1 offset:15360
	s_waitcnt lgkmcnt(7)
	v_mfma_f32_32x32x16_bf16 v[80:95], v[218:221], v[128:131], v[80:95]
	s_waitcnt lgkmcnt(6)
	v_mfma_f32_32x32x16_bf16 v[96:111], v[222:225], v[128:131], v[96:111]
	s_waitcnt lgkmcnt(5)
	v_mfma_f32_32x32x16_bf16 v[80:95], v[226:229], v[132:135], v[80:95]
	s_waitcnt lgkmcnt(4)
	v_mfma_f32_32x32x16_bf16 v[96:111], v[230:233], v[132:135], v[96:111]
	s_waitcnt lgkmcnt(3)
	v_mfma_f32_32x32x16_bf16 v[80:95], v[234:237], v[136:139], v[80:95]
	s_waitcnt lgkmcnt(2)
	v_mfma_f32_32x32x16_bf16 v[96:111], v[238:241], v[136:139], v[96:111]
	s_waitcnt lgkmcnt(1)
	v_mfma_f32_32x32x16_bf16 v[80:95], v[242:245], v[140:143], v[80:95]
	s_waitcnt lgkmcnt(0)
	v_mfma_f32_32x32x16_bf16 v[96:111], v[246:249], v[140:143], v[96:111]
	s_mov_b32 m0, s10
	s_nop 0
	global_load_lds_dwordx4 v[4:5], off
	s_add_i32 m0, s10, 0x2000
	s_nop 0
	global_load_lds_dwordx4 v[6:7], off
	s_add_i32 m0, s10, 0x8000
	s_nop 0
	global_load_lds_dwordx4 v[8:9], off
	s_add_i32 m0, s10, 0xa000
	s_nop 0
	global_load_lds_dwordx4 v[10:11], off
	s_branch .Lmoba_qk_done
